# P1: each XCD writes the bf16 h rows its own in-projection tiles read (producer/consumer XCD affinity), the rows read first written last
# baseline (speedup 1.0000x reference)
.LBB0_153:
	s_mul_i32 s8, s4, 0xc00
	s_ashr_i32 s9, s8, 31
	s_lshl_b64 s[8:9], s[8:9], 2
	v_readlane_b32 s34, v250, 0
	v_readlane_b32 s35, v250, 1
	s_add_u32 s8, s34, s8
	s_addc_u32 s9, s35, s9
	v_lshl_add_u64 v[0:1], s[8:9], 0, v[6:7]
	v_add_co_u32_e32 v0, vcc, 0x1000, v0
	v_lshl_add_u64 v[48:49], s[6:7], 0, v[6:7]
	s_nop 0
	v_addc_co_u32_e32 v1, vcc, 0, v1, vcc
	v_add_co_u32_e32 v20, vcc, 0x1000, v48
	global_load_dwordx4 v[12:15], v[0:1], off offset:256 nt
	s_nop 0
	v_addc_co_u32_e32 v21, vcc, 0, v49, vcc
	v_add_co_u32_e32 v24, vcc, 0x2000, v48
	global_load_dwordx4 v[0:3], v6, s[8:9] offset:256
	global_load_dwordx4 v[16:19], v6, s[6:7]
	v_addc_co_u32_e32 v25, vcc, 0, v49, vcc
	v_add_co_u32_e32 v28, vcc, 0x3000, v48
	global_load_dwordx4 v[20:23], v[20:21], off nt
	s_nop 0
	v_addc_co_u32_e32 v29, vcc, 0, v49, vcc
	v_add_co_u32_e32 v32, vcc, 0x4000, v48
	global_load_dwordx4 v[24:27], v[24:25], off nt
	s_nop 0
	v_addc_co_u32_e32 v33, vcc, 0, v49, vcc
	global_load_dwordx4 v[28:31], v[28:29], off nt
	v_add_co_u32_e32 v36, vcc, 0x5000, v48
	global_load_dwordx4 v[32:35], v[32:33], off nt
	s_nop 0
	v_addc_co_u32_e32 v37, vcc, 0, v49, vcc
	global_load_dwordx4 v[36:39], v[36:37], off nt
	v_add_co_u32_e32 v40, vcc, 0x6000, v48
	s_lshl_b64 s[6:7], s[0:1], 11
	s_nop 0
	v_addc_co_u32_e32 v41, vcc, 0, v49, vcc
	global_load_dwordx4 v[40:43], v[40:41], off nt
	v_add_co_u32_e32 v44, vcc, 0x7000, v48
	v_lshl_add_u64 v[50:51], v[4:5], 0, s[6:7]
	s_cmpk_gt_i32 s23, 0x7ff
	s_cbranch_scc1 .Lp1_noinv
	s_lshr_b32 s1, s23, 8
	s_and_b32 s6, s23, 63
	s_lshl_b32 s6, s6, 3
	s_or_b32 s1, s1, s6
	s_bfe_u32 s6, s23, 0x20006
	s_xor_b32 s6, s6, 3
	s_lshl_b32 s6, s6, 9
	s_or_b32 s23, s1, s6
	s_lshl_b32 s0, s23, 4
.Lp1_noinv:
	s_nop 0
	v_addc_co_u32_e32 v45, vcc, 0, v49, vcc
	global_load_dwordx4 v[44:47], v[44:45], off nt
	v_add_co_u32_e32 v52, vcc, s10, v50
	s_add_i32 s23, s23, s84
	s_nop 0
	v_addc_co_u32_e32 v53, vcc, 0, v51, vcc
	v_add_co_u32_e32 v54, vcc, s11, v50
	s_add_i32 s0, s0, s3
	s_nop 0
	v_addc_co_u32_e32 v55, vcc, 0, v51, vcc
	s_cmpk_gt_i32 s23, 0x807
	s_waitcnt vmcnt(9)
	v_pk_add_f32 v[56:57], v[12:13], 1.0 op_sel_hi:[1,0]
	v_pk_add_f32 v[58:59], v[14:15], 1.0 op_sel_hi:[1,0]
	s_waitcnt vmcnt(7)
	v_pk_fma_f32 v[12:13], v[56:57], v[16:17], v[0:1]
	v_pk_fma_f32 v[14:15], v[58:59], v[18:19], v[2:3]
	v_cvt_pk_bf16_f32 v12, v12, v13
	v_cvt_pk_bf16_f32 v13, v14, v15
	s_waitcnt vmcnt(6)
	v_pk_fma_f32 v[16:17], v[56:57], v[20:21], v[0:1]
	v_pk_fma_f32 v[18:19], v[58:59], v[22:23], v[2:3]
	v_cvt_pk_bf16_f32 v14, v16, v17
	v_cvt_pk_bf16_f32 v15, v18, v19
	global_store_dwordx2 v[50:51], v[12:13], off
	global_store_dwordx2 v[50:51], v[14:15], off offset:2048
	s_waitcnt vmcnt(7)
	v_pk_fma_f32 v[16:17], v[56:57], v[24:25], v[0:1]
	v_pk_fma_f32 v[18:19], v[58:59], v[26:27], v[2:3]
	v_cvt_pk_bf16_f32 v12, v16, v17
	v_cvt_pk_bf16_f32 v13, v18, v19
	s_waitcnt vmcnt(6)
	v_pk_fma_f32 v[14:15], v[56:57], v[28:29], v[0:1]
	v_pk_fma_f32 v[16:17], v[58:59], v[30:31], v[2:3]
	global_store_dwordx2 v[54:55], v[12:13], off offset:-4096
	v_cvt_pk_bf16_f32 v12, v14, v15
	v_cvt_pk_bf16_f32 v13, v16, v17
	s_waitcnt vmcnt(6)
	v_pk_fma_f32 v[14:15], v[56:57], v[32:33], v[0:1]
	v_pk_fma_f32 v[16:17], v[58:59], v[34:35], v[2:3]
	global_store_dwordx2 v[52:53], v[12:13], off offset:2048
	v_cvt_pk_bf16_f32 v12, v14, v15
	v_cvt_pk_bf16_f32 v13, v16, v17
	s_waitcnt vmcnt(6)
	v_pk_fma_f32 v[14:15], v[56:57], v[36:37], v[0:1]
	global_store_dwordx2 v[54:55], v[12:13], off
	v_cvt_pk_bf16_f32 v12, v14, v15
	v_pk_fma_f32 v[14:15], v[58:59], v[38:39], v[2:3]
	s_waitcnt vmcnt(5)
	v_pk_fma_f32 v[16:17], v[58:59], v[46:47], v[2:3]
	v_cvt_pk_bf16_f32 v13, v14, v15
	global_store_dwordx2 v[54:55], v[12:13], off offset:2048
	v_pk_fma_f32 v[12:13], v[56:57], v[40:41], v[0:1]
	v_pk_fma_f32 v[14:15], v[58:59], v[42:43], v[2:3]
	v_cvt_pk_bf16_f32 v12, v12, v13
	v_cvt_pk_bf16_f32 v13, v14, v15
	v_add_co_u32_e32 v14, vcc, s12, v50
	s_nop 1
	v_addc_co_u32_e32 v15, vcc, 0, v51, vcc
	v_add_co_u32_e32 v52, vcc, s13, v50
	s_nop 1
	v_addc_co_u32_e32 v53, vcc, 0, v51, vcc
	v_add_co_u32_e32 v20, vcc, s19, v48
	global_store_dwordx2 v[52:53], v[12:13], off offset:-4096
	s_nop 0
	v_addc_co_u32_e32 v21, vcc, 0, v49, vcc
	v_add_co_u32_e32 v28, vcc, s20, v48
	v_pk_fma_f32 v[12:13], v[56:57], v[44:45], v[0:1]
	s_nop 0
	v_addc_co_u32_e32 v29, vcc, 0, v49, vcc
	v_cvt_pk_bf16_f32 v12, v12, v13
	v_cvt_pk_bf16_f32 v13, v16, v17
	v_add_co_u32_e32 v36, vcc, s21, v48
	global_store_dwordx2 v[14:15], v[12:13], off offset:2048
	s_nop 0
	v_addc_co_u32_e32 v37, vcc, 0, v49, vcc
	global_load_dwordx4 v[12:15], v[20:21], off offset:-4096 nt
	global_load_dwordx4 v[16:19], v[20:21], off nt
	s_nop 0
	global_load_dwordx4 v[20:23], v[28:29], off offset:-4096 nt
	global_load_dwordx4 v[24:27], v[28:29], off nt
	s_nop 0
	global_load_dwordx4 v[28:31], v[36:37], off offset:-4096 nt
	global_load_dwordx4 v[32:35], v[36:37], off nt
	v_add_co_u32_e32 v44, vcc, s22, v48
	s_waitcnt vmcnt(5)
	v_pk_fma_f32 v[12:13], v[56:57], v[12:13], v[0:1]
	v_addc_co_u32_e32 v45, vcc, 0, v49, vcc
	global_load_dwordx4 v[36:39], v[44:45], off offset:-4096 nt
	global_load_dwordx4 v[40:43], v[44:45], off nt
	v_add_co_u32_e32 v44, vcc, s16, v50
	v_pk_fma_f32 v[14:15], v[58:59], v[14:15], v[2:3]
	s_nop 0
	v_addc_co_u32_e32 v45, vcc, 0, v51, vcc
	v_add_co_u32_e32 v46, vcc, s17, v50
	s_waitcnt vmcnt(6)
	v_pk_fma_f32 v[16:17], v[56:57], v[16:17], v[0:1]
	v_pk_fma_f32 v[18:19], v[58:59], v[18:19], v[2:3]
	s_waitcnt vmcnt(5)
	v_pk_fma_f32 v[20:21], v[56:57], v[20:21], v[0:1]
	v_pk_fma_f32 v[22:23], v[58:59], v[22:23], v[2:3]
	s_waitcnt vmcnt(4)
	v_pk_fma_f32 v[24:25], v[56:57], v[24:25], v[0:1]
	v_pk_fma_f32 v[26:27], v[58:59], v[26:27], v[2:3]
	s_waitcnt vmcnt(3)
	v_pk_fma_f32 v[28:29], v[56:57], v[28:29], v[0:1]
	v_pk_fma_f32 v[30:31], v[58:59], v[30:31], v[2:3]
	s_waitcnt vmcnt(2)
	v_pk_fma_f32 v[32:33], v[56:57], v[32:33], v[0:1]
	v_pk_fma_f32 v[34:35], v[58:59], v[34:35], v[2:3]
	v_cvt_pk_bf16_f32 v12, v12, v13
	v_cvt_pk_bf16_f32 v13, v14, v15
	v_addc_co_u32_e32 v47, vcc, 0, v51, vcc
	v_cvt_pk_bf16_f32 v14, v16, v17
	v_cvt_pk_bf16_f32 v15, v18, v19
	v_cvt_pk_bf16_f32 v16, v20, v21
	v_cvt_pk_bf16_f32 v17, v22, v23
	v_cvt_pk_bf16_f32 v18, v24, v25
	v_cvt_pk_bf16_f32 v19, v26, v27
	v_cvt_pk_bf16_f32 v20, v28, v29
	v_cvt_pk_bf16_f32 v21, v30, v31
	v_cvt_pk_bf16_f32 v22, v32, v33
	v_cvt_pk_bf16_f32 v23, v34, v35
	global_store_dwordx2 v[52:53], v[12:13], off
	global_store_dwordx2 v[52:53], v[14:15], off offset:2048
	global_store_dwordx2 v[46:47], v[16:17], off offset:-4096
	global_store_dwordx2 v[44:45], v[18:19], off offset:2048
	global_store_dwordx2 v[46:47], v[20:21], off
	global_store_dwordx2 v[46:47], v[22:23], off offset:2048
	s_waitcnt vmcnt(7)
	v_pk_fma_f32 v[12:13], v[58:59], v[38:39], v[2:3]
	v_pk_fma_f32 v[36:37], v[56:57], v[36:37], v[0:1]
	v_cvt_pk_bf16_f32 v25, v12, v13
	v_add_co_u32_e32 v12, vcc, s18, v50
	s_waitcnt vmcnt(6)
	v_pk_fma_f32 v[0:1], v[56:57], v[40:41], v[0:1]
	v_pk_fma_f32 v[2:3], v[58:59], v[42:43], v[2:3]
	v_cvt_pk_bf16_f32 v24, v36, v37
	v_addc_co_u32_e32 v13, vcc, 0, v51, vcc
	v_cvt_pk_bf16_f32 v0, v0, v1
	v_cvt_pk_bf16_f32 v1, v2, v3
	global_store_dwordx2 v[12:13], v[24:25], off
	global_store_dwordx2 v[12:13], v[0:1], off offset:2048
	s_cbranch_scc1 .LBB0_158

.LBB0_156:
	s_andn2_b64 vcc, exec, s[8:9]
	s_cbranch_vccnz .LBB0_153
	s_and_b32 s1, s23, 7
	s_lshl_b32 s1, s1, 8
	s_bfe_u32 s4, s23, 0x60003
	s_or_b32 s1, s1, s4
	s_lshr_b32 s4, s23, 9
	s_xor_b32 s4, s4, 3
	s_lshl_b32 s4, s4, 6
	s_or_b32 s23, s1, s4
	s_lshl_b32 s0, s23, 4
	s_ashr_i32 s1, s0, 31
	s_lshl_b64 s[6:7], s[0:1], 12
	s_add_u32 s6, s36, s6
	s_addc_u32 s7, s37, s7
	s_ashr_i32 s4, s23, 9
	s_branch .LBB0_153
